# speedup vs baseline: 1.0034x; 1.0034x over previous
; #define PG8_STAGE(bufoff, gbase, voff) do { _Pragma("unroll") for (int _i = 0; _i < 2; ++_i) \
;         __builtin_amdgcn_global_load_lds((const unsigned*)((const char*)(gbase) + (voff)[_i]), (LAS unsigned*)(lds + (bufoff) + ldsw + _i * 8192), 16, 0, 0); } while (0)
; #define PG8_LDA(dst, b, h) do { _Pragma("unroll") for (int m = 0; m < 4; ++m) _Pragma("unroll") for (int k = 0; k < 2; ++k) dst[m][k] = *(const LAS bf16x8*)(lds + PG8_SA(b, h) + aoff + m * 2048 + k * 1024); } while (0)
; #define PG8_LDB(dst, b, h) do { _Pragma("unroll") for (int n = 0; n < 2; ++n) _Pragma("unroll") for (int k = 0; k < 2; ++k) dst[n][k] = *(const LAS bf16x8*)(lds + PG8_SB(b, h) + boff + n * 2048 + k * 1024); } while (0)
; #define PG8_MMA(ai, bj, At, Bt) do { __builtin_amdgcn_s_setprio(1); _Pragma("unroll") for (int m = 0; m < 4; ++m) _Pragma("unroll") for (int n = 0; n < 2; ++n) _Pragma("unroll") for (int k = 0; k < 2; ++k) \
;         acc[ai][bj][m][n] = __builtin_amdgcn_mfma_f32_16x16x32_bf16(Bt[n][k], At[m][k], acc[ai][bj][m][n], 0, 0, 0); __builtin_amdgcn_s_setprio(0); } while (0)
; #define PG8_WAIT_V(n) asm volatile("s_waitcnt vmcnt(" #n ")" ::: "memory")
; #define PG8_BAR __builtin_amdgcn_s_barrier()
; template <class Epi, bool NARROW = false>
; __device__ __forceinline__ void gemm_phase(const Ctx cx, LAS unsigned char* lds, const Gemm g, const StaticOrder& S, const Epi& E) {
;     ...
;             const bool last = (t == nt - 2);
;             const char* a1 = cA + (size_t)(t + 1) * kstep;
;             const char* a2 = last ? nA : cA + (size_t)(t + 2) * kstep; const char* b2 = last ? nB : cB + (size_t)(t + 2) * kstep;
;             const char* a3 = a2 + kstep; const char* b3 = b2 + kstep;
;             PG8_LDB(B0, 0, 0); if constexpr (!NARROW) PG8_LDB(B1, 0, 1); PG8_SCHED; PG8_LDA(At, 0, 0); PG8_STAGE(PG8_SA(1, 1), a1 + hstepA, voffA);
;             PG8_WAIT_V(8); PG8_WAIT_L(0); PG8_BAR; if constexpr (NARROW) { if (wc < 2) PG8_MMA(0, 0, At, B0); } else { PG8_MMA(0, 0, At, B0); PG8_MMA(0, 1, At, B1); } PG8_BAR; PG8_SCHED;
;             PG8_LDA(At, 0, 1); PG8_STAGE(PG8_SB(0, 0), b2, voffB); PG8_STAGE(PG8_SB(0, 1), b2 + hstepB, voffB); PG8_STAGE(PG8_SA(0, 0), a2, voffA);
;             PG8_WAIT_V(8); PG8_WAIT_L(0); PG8_BAR; if constexpr (NARROW) { if (wc < 2) PG8_MMA(1, 0, At, B0); } else { PG8_MMA(1, 0, At, B0); PG8_MMA(1, 1, At, B1); } PG8_BAR; PG8_SCHED;
.LBB0_348:
	s_add_u32 s4, s34, 0xfff80080
	s_addc_u32 s5, s35, -1
	s_cmp_eq_u32 s46, 28
	s_cselect_b32 s37, s23, s5
	s_cselect_b32 s36, s33, s4
	s_cselect_b32 s5, s21, s45
	s_cselect_b32 s4, s40, s44
	s_barrier
	s_mov_b32 m0, s42
	v_lshl_add_u64 v[126:127], s[4:5], 0, v[116:117]
	s_add_u32 s48, s4, 0x80000
	s_waitcnt lgkmcnt(0)
	ds_read_b128 v[108:111], v137 offset:16384
	ds_read_b128 v[112:115], v137 offset:17408
	ds_read_b128 v[100:103], v137 offset:18432
	ds_read_b128 v[104:107], v137 offset:19456
	ds_read_b128 v[92:95], v137 offset:20480
	ds_read_b128 v[96:99], v137 offset:21504
	ds_read_b128 v[84:87], v137 offset:22528
	ds_read_b128 v[88:91], v137 offset:23552
	global_load_lds_dwordx4 v[126:127], off
	v_lshl_add_u64 v[128:129], s[4:5], 0, v[120:121]
	s_mov_b32 m0, s43
	s_addc_u32 s49, s5, 0
	global_load_lds_dwordx4 v181, s[80:81]
	v_lshl_add_u64 v[130:131], s[48:49], 0, v[116:117]
	s_mov_b32 m0, s62
	v_lshl_add_u64 v[132:133], s[36:37], 0, v[118:119]
	global_load_lds_dwordx4 v181, s[80:81]
	v_lshl_add_u64 v[130:131], s[48:49], 0, v[120:121]
	s_mov_b32 m0, s63
	s_and_b64 vcc, exec, s[6:7]
	global_load_lds_dwordx4 v181, s[80:81]
	v_lshl_add_u64 v[130:131], s[36:37], 0, v[180:181]
	s_mov_b32 m0, s31
	s_nop 0
	global_load_lds_dwordx4 v[130:131], off
	s_mov_b32 m0, s64
	s_nop 0
	global_load_lds_dwordx4 v[132:133], off
	s_waitcnt vmcnt(8)
	s_waitcnt lgkmcnt(0)
	s_barrier
	s_cbranch_vccnz .LBB0_350
	s_setprio 1
	s_waitcnt lgkmcnt(0)
	v_mfma_f32_16x16x32_bf16 v[32:35], v[68:71], v[108:111], v[32:35]
	v_mfma_f32_16x16x32_bf16 v[28:31], v[76:79], v[108:111], v[28:31]
	v_mfma_f32_16x16x32_bf16 v[24:27], v[68:71], v[100:103], v[24:27]
	v_mfma_f32_16x16x32_bf16 v[20:23], v[76:79], v[100:103], v[20:23]
	v_mfma_f32_16x16x32_bf16 v[16:19], v[68:71], v[92:95], v[16:19]
	v_mfma_f32_16x16x32_bf16 v[12:15], v[76:79], v[92:95], v[12:15]
	v_mfma_f32_16x16x32_bf16 v[8:11], v[68:71], v[84:87], v[8:11]
	v_mfma_f32_16x16x32_bf16 v[4:7], v[76:79], v[84:87], v[4:7]
	v_mfma_f32_16x16x32_bf16 v[32:35], v[72:75], v[112:115], v[32:35]
	v_mfma_f32_16x16x32_bf16 v[28:31], v[80:83], v[112:115], v[28:31]
	v_mfma_f32_16x16x32_bf16 v[24:27], v[72:75], v[104:107], v[24:27]
	v_mfma_f32_16x16x32_bf16 v[20:23], v[80:83], v[104:107], v[20:23]
	v_mfma_f32_16x16x32_bf16 v[16:19], v[72:75], v[96:99], v[16:19]
	v_mfma_f32_16x16x32_bf16 v[12:15], v[80:83], v[96:99], v[12:15]
	v_mfma_f32_16x16x32_bf16 v[8:11], v[72:75], v[88:91], v[8:11]
	v_mfma_f32_16x16x32_bf16 v[4:7], v[80:83], v[88:91], v[4:7]
	s_setprio 0

; #define PG8_STAGE(bufoff, gbase, voff) do { _Pragma("unroll") for (int _i = 0; _i < 2; ++_i) \
;         __builtin_amdgcn_global_load_lds((const unsigned*)((const char*)(gbase) + (voff)[_i]), (LAS unsigned*)(lds + (bufoff) + ldsw + _i * 8192), 16, 0, 0); } while (0)
; #define PG8_LDA(dst, b, h) do { _Pragma("unroll") for (int m = 0; m < 4; ++m) _Pragma("unroll") for (int k = 0; k < 2; ++k) dst[m][k] = *(const LAS bf16x8*)(lds + PG8_SA(b, h) + aoff + m * 2048 + k * 1024); } while (0)
; #define PG8_LDB(dst, b, h) do { _Pragma("unroll") for (int n = 0; n < 2; ++n) _Pragma("unroll") for (int k = 0; k < 2; ++k) dst[n][k] = *(const LAS bf16x8*)(lds + PG8_SB(b, h) + boff + n * 2048 + k * 1024); } while (0)
; #define PG8_MMA(ai, bj, At, Bt) do { __builtin_amdgcn_s_setprio(1); _Pragma("unroll") for (int m = 0; m < 4; ++m) _Pragma("unroll") for (int n = 0; n < 2; ++n) _Pragma("unroll") for (int k = 0; k < 2; ++k) \
;         acc[ai][bj][m][n] = __builtin_amdgcn_mfma_f32_16x16x32_bf16(Bt[n][k], At[m][k], acc[ai][bj][m][n], 0, 0, 0); __builtin_amdgcn_s_setprio(0); } while (0)
; #define PG8_WAIT_V(n) asm volatile("s_waitcnt vmcnt(" #n ")" ::: "memory")
; #define PG8_WAIT_L(n) asm volatile("s_waitcnt lgkmcnt(" #n ")" ::: "memory")
; #define PG8_BAR __builtin_amdgcn_s_barrier()
; #define PG8_SCHED __builtin_amdgcn_sched_barrier(0)
; template <class Epi, bool NARROW = false>
; __device__ __forceinline__ void gemm_phase(const Ctx cx, LAS unsigned char* lds, const Gemm g, const StaticOrder& S, const Epi& E) {
;     ...
;             PG8_LDB(B0, 1, 0); if constexpr (!NARROW) PG8_LDB(B1, 1, 1); PG8_SCHED; PG8_LDA(At, 1, 0); PG8_STAGE(PG8_SA(0, 1), a2 + hstepA, voffA);
;             PG8_WAIT_V(8); PG8_WAIT_L(0); PG8_BAR; if constexpr (NARROW) { if (wc < 2) PG8_MMA(0, 0, At, B0); } else { PG8_MMA(0, 0, At, B0); PG8_MMA(0, 1, At, B1); } PG8_BAR; PG8_SCHED;
;             PG8_LDA(At, 1, 1); PG8_STAGE(PG8_SB(1, 0), b3, voffB); PG8_STAGE(PG8_SB(1, 1), b3 + hstepB, voffB); PG8_STAGE(PG8_SA(1, 0), a3, voffA);
;             PG8_WAIT_V(8); PG8_WAIT_L(0); PG8_BAR; if constexpr (NARROW) { if (wc < 2) PG8_MMA(1, 0, At, B0); } else { PG8_MMA(1, 0, At, B0); PG8_MMA(1, 1, At, B1); } PG8_BAR; PG8_SCHED;
.LBB0_352:
	s_barrier
	s_mov_b32 m0, s72
	v_lshl_add_u64 v[126:127], v[126:127], 0, s[98:99]
	s_add_u32 s4, s4, 0x80080
	s_waitcnt lgkmcnt(0)
	ds_read_b128 v[108:111], v137 offset:49152
	ds_read_b128 v[112:115], v137 offset:50176
	ds_read_b128 v[100:103], v137 offset:51200
	ds_read_b128 v[104:107], v137 offset:52224
	ds_read_b128 v[92:95], v137 offset:53248
	ds_read_b128 v[96:99], v137 offset:54272
	ds_read_b128 v[84:87], v137 offset:55296
	ds_read_b128 v[88:91], v137 offset:56320
	global_load_lds_dwordx4 v[126:127], off
	v_lshl_add_u64 v[126:127], v[128:129], 0, s[98:99]
	s_mov_b32 m0, s73
	s_addc_u32 s5, s5, 0
	global_load_lds_dwordx4 v181, s[80:81]
	v_lshl_add_u64 v[126:127], s[4:5], 0, v[116:117]
	s_mov_b32 m0, s86
	s_and_b64 vcc, exec, s[6:7]
	global_load_lds_dwordx4 v181, s[80:81]
	v_lshl_add_u64 v[126:127], s[4:5], 0, v[120:121]
	s_mov_b32 m0, s87
	s_nop 0
	global_load_lds_dwordx4 v181, s[80:81]
	v_lshl_add_u64 v[126:127], v[130:131], 0, s[98:99]
	s_mov_b32 m0, s82
	s_nop 0
	global_load_lds_dwordx4 v[126:127], off
	v_lshl_add_u64 v[126:127], v[132:133], 0, s[98:99]
	s_mov_b32 m0, s83
	s_nop 0
	global_load_lds_dwordx4 v[126:127], off
	s_waitcnt vmcnt(8)
	s_waitcnt lgkmcnt(0)
	s_barrier
	s_cbranch_vccnz .LBB0_345
	s_setprio 1
	s_waitcnt lgkmcnt(0)
	v_mfma_f32_16x16x32_bf16 v[32:35], v[68:71], v[108:111], v[32:35]
	v_mfma_f32_16x16x32_bf16 v[28:31], v[76:79], v[108:111], v[28:31]
	v_mfma_f32_16x16x32_bf16 v[24:27], v[68:71], v[100:103], v[24:27]
	v_mfma_f32_16x16x32_bf16 v[20:23], v[76:79], v[100:103], v[20:23]
	v_mfma_f32_16x16x32_bf16 v[16:19], v[68:71], v[92:95], v[16:19]
	v_mfma_f32_16x16x32_bf16 v[12:15], v[76:79], v[92:95], v[12:15]
	v_mfma_f32_16x16x32_bf16 v[8:11], v[68:71], v[84:87], v[8:11]
	v_mfma_f32_16x16x32_bf16 v[4:7], v[76:79], v[84:87], v[4:7]
	v_mfma_f32_16x16x32_bf16 v[32:35], v[72:75], v[112:115], v[32:35]
	v_mfma_f32_16x16x32_bf16 v[28:31], v[80:83], v[112:115], v[28:31]
	v_mfma_f32_16x16x32_bf16 v[24:27], v[72:75], v[104:107], v[24:27]
	v_mfma_f32_16x16x32_bf16 v[20:23], v[80:83], v[104:107], v[20:23]
	v_mfma_f32_16x16x32_bf16 v[16:19], v[72:75], v[96:99], v[16:19]
	v_mfma_f32_16x16x32_bf16 v[12:15], v[80:83], v[96:99], v[12:15]
	v_mfma_f32_16x16x32_bf16 v[8:11], v[72:75], v[88:91], v[8:11]
	v_mfma_f32_16x16x32_bf16 v[4:7], v[80:83], v[88:91], v[4:7]
	s_setprio 0
	s_branch .LBB0_345
